# operand row-pitch padding: x1 bf16 copy stored with 4224-byte row pitch at ws+456MiB, up-GEMM A addressing follows
# baseline (speedup 1.0000x reference)
; __device__ __forceinline__ unsigned pk2(float lo, float hi) { unsigned r; asm("v_cvt_pk_bf16_f32 %0, %1, %2" : "=v"(r) : "v"(lo), "v"(hi)); return r; }
; __device__ __forceinline__ void phase_ln(const float* res, const bf16_t* br, float* out, const float* gam, const float* bet, bf16_t* xb) {
;     const int tid = threadIdx.x, lane = tid & 63, wave = tid >> 6;
;     for (int row = blockIdx.x * NWAVES + wave; row < T; row += gridDim.x * NWAVES) {
;         const f32x4* xr = (const f32x4*)(res + (size_t)row * DM) + lane; const u32x2* brr = (const u32x2*)(br + (size_t)row * DM) + lane;
;         f32x4 v[8]; float s = 0.f;
; #pragma unroll
;         for (int j = 0; j < 8; ++j) { const f32x4 xv = __builtin_nontemporal_load(xr + 64 * j); const u32x2 bw = __builtin_nontemporal_load(brr + 64 * j);
;             v[j] = xv * ALPHA + (f32x4){bflo(bw.x), bfhi(bw.x), bflo(bw.y), bfhi(bw.y)}; s += (v[j][0] + v[j][1]) + (v[j][2] + v[j][3]); }
;         const float mu = wave_sum(s) * (1.0f / DM); float q = 0.f;
; #pragma unroll
;         for (int j = 0; j < 8; ++j) { v[j] = v[j] - mu; q += (v[j][0] * v[j][0] + v[j][1] * v[j][1]) + (v[j][2] * v[j][2] + v[j][3] * v[j][3]); }
;         const float rstd = 1.0f / sqrtf(wave_sum(q) * (1.0f / DM) + LN_EPS);
;         f32x4* orow = (f32x4*)(out + (size_t)row * DM) + lane;
; #pragma unroll
;         for (int j = 0; j < 8; ++j) { const f32x4 gv = *((const f32x4*)gam + 64 * j + lane), bv = *((const f32x4*)bet + 64 * j + lane);
;             const f32x4 y = v[j] * rstd * gv + bv; __builtin_nontemporal_store(y, orow + 64 * j);
;             if (xb) { u32x2 wv; wv.x = pk2(y[0], y[1]); wv.y = pk2(y[2], y[3]); __builtin_nontemporal_store(wv, (u32x2*)(xb + (size_t)row * DM) + 64 * j + lane); } }
.LBB0_811:
	v_readlane_b32 s4, v246, 12
	s_cmp_lt_i32 s4, 9
	s_cselect_b64 s[2:3], -1, 0
	s_and_b64 s[0:1], s[2:3], s[0:1]
	s_andn2_b64 vcc, exec, s[0:1]
	v_readlane_b32 s5, v246, 13
	v_readlane_b32 s6, v246, 14
	v_readlane_b32 s7, v246, 15
	s_cbranch_vccnz .LBB0_816
	v_readlane_b32 s0, v246, 0
	v_readlane_b32 s1, v246, 1
	s_nop 0
	v_lshl_add_u32 v0, s0, 3, v159
	s_mov_b32 s0, 0x8000
	v_cmp_gt_i32_e32 vcc, s0, v0
	s_and_saveexec_b64 s[4:5], vcc
	s_cbranch_execz .LBB0_815
	v_and_b32_e32 v1, 63, v144
	s_waitcnt vmcnt(0)
	v_lshlrev_b32_e32 v10, 4, v1
	v_lshlrev_b32_e32 v4, 3, v1
	v_mbcnt_lo_u32_b32 v1, -1, 0
	v_mbcnt_hi_u32_b32 v1, -1, v1
	v_and_b32_e32 v6, 64, v1
	v_add_u32_e32 v6, 64, v6
	v_xor_b32_e32 v7, 1, v1
	v_cmp_lt_i32_e32 vcc, v7, v6
	v_readlane_b32 s8, v246, 2
	v_mov_b32_e32 v11, 0
	v_cndmask_b32_e32 v7, v1, v7, vcc
	v_lshlrev_b32_e32 v66, 2, v7
	v_xor_b32_e32 v7, 2, v1
	v_cmp_lt_i32_e32 vcc, v7, v6
	v_readlane_b32 s0, v246, 10
	v_readlane_b32 s9, v246, 3
	v_cndmask_b32_e32 v7, v1, v7, vcc
	v_lshlrev_b32_e32 v67, 2, v7
	v_xor_b32_e32 v7, 4, v1
	v_cmp_lt_i32_e32 vcc, v7, v6
	v_readlane_b32 s10, v246, 4
	v_readlane_b32 s11, v246, 5
	v_cndmask_b32_e32 v7, v1, v7, vcc
	v_lshlrev_b32_e32 v68, 2, v7
	v_xor_b32_e32 v7, 8, v1
	v_cmp_lt_i32_e32 vcc, v7, v6
	v_readlane_b32 s12, v246, 6
	v_readlane_b32 s13, v246, 7
	v_cndmask_b32_e32 v7, v1, v7, vcc
	v_lshlrev_b32_e32 v69, 2, v7
	v_xor_b32_e32 v7, 16, v1
	v_cmp_lt_i32_e32 vcc, v7, v6
	v_readlane_b32 s14, v246, 8
	v_readlane_b32 s15, v246, 9
	v_cndmask_b32_e32 v7, v1, v7, vcc
	v_lshlrev_b32_e32 v70, 2, v7
	v_xor_b32_e32 v7, 32, v1
	v_cmp_lt_i32_e32 vcc, v7, v6
	s_waitcnt lgkmcnt(0)
	v_lshl_add_u64 v[2:3], s[16:17], 0, v[10:11]
	v_mov_b32_e32 v5, v11
	v_readlane_b32 s1, v246, 11
	v_cndmask_b32_e32 v1, v1, v7, vcc
	v_lshl_add_u64 v[6:7], s[14:15], 0, v[10:11]
	v_readlane_b32 s8, v246, 25
	v_lshl_add_u64 v[12:13], s[0:1], 0, v[4:5]
	s_mov_b64 s[0:1], 0x10800000
	v_readlane_b32 s9, v246, 26
	v_readlane_b32 s14, v246, 31
	v_readlane_b32 s15, v246, 32
	v_readlane_b32 s16, v246, 33
	v_readlane_b32 s17, v246, 34
	v_lshl_add_u64 v[4:5], v[12:13], 0, s[0:1]
	s_mov_b64 s[6:7], s[14:15]
	s_mov_b64 s[8:9], s[16:17]
	s_mov_b64 s[0:1], 0x1c800000
	v_lshl_add_u64 v[8:9], s[6:7], 0, v[10:11]
	v_lshl_add_u64 v[10:11], s[8:9], 0, v[10:11]
	v_lshl_add_u64 v[12:13], v[12:13], 0, s[0:1]
	s_mov_b64 s[0:1], 0x1000
	v_lshl_add_u64 v[14:15], v[8:9], 0, s[0:1]
	v_lshl_add_u64 v[16:17], v[10:11], 0, s[0:1]
	s_mov_b64 s[0:1], 0x1400
	v_lshl_add_u64 v[18:19], v[8:9], 0, s[0:1]
	v_lshl_add_u64 v[20:21], v[10:11], 0, s[0:1]
	s_mov_b64 s[0:1], 0x1800
	v_readlane_b32 s10, v246, 27
	v_readlane_b32 s11, v246, 28
	v_readlane_b32 s12, v246, 29
	v_lshl_add_u64 v[22:23], v[8:9], 0, s[0:1]
	v_lshl_add_u64 v[24:25], v[10:11], 0, s[0:1]
	s_mov_b64 s[0:1], 0x1c00
	v_lshlrev_b32_e32 v71, 2, v1
	v_lshl_add_u64 v[26:27], v[8:9], 0, s[0:1]
	v_lshl_add_u64 v[28:29], v[10:11], 0, s[0:1]
	s_lshl_b32 s9, s34, 3
	s_mov_b64 s[6:7], 0
	s_mov_b32 s8, 0x3f9837f0
	s_movk_i32 s10, 0x1000
	v_mov_b32_e32 v72, 0x3727c5ac
	s_mov_b32 s11, 0xf800000
	v_mov_b32_e32 v73, 0x260
	s_movk_i32 s12, 0x7fff
	v_readlane_b32 s13, v246, 30
	v_readlane_b32 s18, v246, 35
	v_readlane_b32 s19, v246, 36
	v_readlane_b32 s20, v246, 37
	v_readlane_b32 s21, v246, 38
	v_readlane_b32 s22, v246, 39
	v_readlane_b32 s23, v246, 40
	global_load_dwordx4 v[160:163], v[8:9], off
	global_load_dwordx4 v[164:167], v[10:11], off
	global_load_dwordx4 v[168:171], v[8:9], off offset:1024
	global_load_dwordx4 v[172:175], v[10:11], off offset:1024
	global_load_dwordx4 v[176:179], v[8:9], off offset:2048
	global_load_dwordx4 v[180:183], v[10:11], off offset:2048
	global_load_dwordx4 v[184:187], v[8:9], off offset:3072
	global_load_dwordx4 v[188:191], v[10:11], off offset:3072
	global_load_dwordx4 v[192:195], v[14:15], off
	global_load_dwordx4 v[196:199], v[16:17], off
	global_load_dwordx4 v[200:203], v[18:19], off
	global_load_dwordx4 v[204:207], v[20:21], off
	global_load_dwordx4 v[208:211], v[22:23], off
	global_load_dwordx4 v[212:215], v[24:25], off
	global_load_dwordx4 v[216:219], v[26:27], off
	global_load_dwordx4 v[220:223], v[28:29], off
	s_waitcnt vmcnt(0)
.LBB0_814:
	v_ashrrev_i32_e32 v1, 31, v0
	v_lshlrev_b64 v[30:31], 12, v[0:1]
	v_lshl_add_u64 v[50:51], v[4:5], 0, v[30:31]
	v_lshlrev_b64 v[48:49], 13, v[0:1]
	global_load_dwordx2 v[52:53], v[50:51], off nt
	global_load_dwordx2 v[54:55], v[50:51], off offset:512 nt
	global_load_dwordx2 v[56:57], v[50:51], off offset:1024 nt
	global_load_dwordx2 v[58:59], v[50:51], off offset:1536 nt
	global_load_dwordx2 v[60:61], v[50:51], off offset:2048 nt
	global_load_dwordx2 v[62:63], v[50:51], off offset:2560 nt
	v_lshl_add_u64 v[64:65], v[2:3], 0, v[48:49]
	global_load_dwordx4 v[32:35], v[64:65], off nt
	global_load_dwordx4 v[36:39], v[64:65], off offset:1024 nt
	global_load_dwordx4 v[40:43], v[64:65], off offset:2048 nt
	global_load_dwordx4 v[44:47], v[64:65], off offset:3072 nt
	v_add_co_u32_e32 v64, vcc, s10, v64
	v_add_u32_e32 v0, s9, v0
	s_nop 0
	v_addc_co_u32_e32 v65, vcc, 0, v65, vcc
	global_load_dwordx4 v[74:77], v[64:65], off nt
	global_load_dwordx4 v[78:81], v[64:65], off offset:1024 nt
	global_load_dwordx2 v[90:91], v[50:51], off offset:3072 nt
	global_load_dwordx4 v[82:85], v[64:65], off offset:2048 nt
	global_load_dwordx2 v[92:93], v[50:51], off offset:3584 nt
	global_load_dwordx4 v[86:89], v[64:65], off offset:3072 nt
	s_waitcnt vmcnt(15)
	v_lshlrev_b32_e32 v50, 16, v52
	v_and_b32_e32 v51, 0xffff0000, v52
	v_lshlrev_b32_e32 v52, 16, v53
	v_and_b32_e32 v53, 0xffff0000, v53
	s_waitcnt vmcnt(14)
; __device__ __forceinline__ void phase_ln(const float* res, const bf16_t* br, float* out, const float* gam, const float* bet, bf16_t* xb) {
;     ...
;         for (int j = 0; j < 8; ++j) { const f32x4 xv = __builtin_nontemporal_load(xr + 64 * j); const u32x2 bw = __builtin_nontemporal_load(brr + 64 * j);
;             v[j] = xv * ALPHA + (f32x4){bflo(bw.x), bfhi(bw.x), bflo(bw.y), bfhi(bw.y)}; s += (v[j][0] + v[j][1]) + (v[j][2] + v[j][3]); }
;         const float mu = wave_sum(s) * (1.0f / DM); float q = 0.f;
	v_lshlrev_b32_e32 v94, 16, v54
	v_and_b32_e32 v95, 0xffff0000, v54
	v_lshlrev_b32_e32 v54, 16, v55
	v_and_b32_e32 v55, 0xffff0000, v55
	s_waitcnt vmcnt(13)
	v_lshlrev_b32_e32 v96, 16, v56
	v_and_b32_e32 v97, 0xffff0000, v56
	v_lshlrev_b32_e32 v56, 16, v57
	v_and_b32_e32 v57, 0xffff0000, v57
	s_waitcnt vmcnt(12)
	v_lshlrev_b32_e32 v98, 16, v58
	v_and_b32_e32 v99, 0xffff0000, v58
	v_lshlrev_b32_e32 v100, 16, v59
	v_and_b32_e32 v101, 0xffff0000, v59
	s_waitcnt vmcnt(11)
	v_lshlrev_b32_e32 v102, 16, v60
	v_and_b32_e32 v103, 0xffff0000, v60
	v_lshlrev_b32_e32 v104, 16, v61
	v_and_b32_e32 v105, 0xffff0000, v61
	s_waitcnt vmcnt(10)
	v_lshlrev_b32_e32 v106, 16, v62
	v_and_b32_e32 v107, 0xffff0000, v62
	v_lshlrev_b32_e32 v108, 16, v63
	v_and_b32_e32 v109, 0xffff0000, v63
	s_waitcnt vmcnt(9)
	v_pk_fma_f32 v[62:63], v[34:35], s[8:9], v[52:53] op_sel_hi:[1,0,1]
	v_pk_fma_f32 v[64:65], v[32:33], s[8:9], v[50:51] op_sel_hi:[1,0,1]
	s_waitcnt vmcnt(8)
	v_pk_fma_f32 v[58:59], v[38:39], s[8:9], v[54:55] op_sel_hi:[1,0,1]
	v_pk_fma_f32 v[60:61], v[36:37], s[8:9], v[94:95] op_sel_hi:[1,0,1]
	s_waitcnt vmcnt(7)
	v_pk_fma_f32 v[54:55], v[42:43], s[8:9], v[56:57] op_sel_hi:[1,0,1]
	v_pk_fma_f32 v[56:57], v[40:41], s[8:9], v[96:97] op_sel_hi:[1,0,1]
	s_waitcnt vmcnt(6)
	v_pk_fma_f32 v[50:51], v[46:47], s[8:9], v[100:101] op_sel_hi:[1,0,1]
	v_pk_fma_f32 v[52:53], v[44:45], s[8:9], v[98:99] op_sel_hi:[1,0,1]
	v_mov_b32_e32 v32, v64
	v_mov_b32_e32 v33, v60
	v_mov_b32_e32 v34, v65
	v_mov_b32_e32 v35, v61
	v_mov_b32_e32 v44, v62
	v_mov_b32_e32 v45, v58
	v_mov_b32_e32 v46, v63
	v_mov_b32_e32 v47, v59
	s_waitcnt vmcnt(5)
	v_pk_fma_f32 v[40:41], v[76:77], s[8:9], v[104:105] op_sel_hi:[1,0,1]
	v_pk_fma_f32 v[42:43], v[74:75], s[8:9], v[102:103] op_sel_hi:[1,0,1]
	v_pk_mov_b32 v[74:75], v[56:57], v[54:55] op_sel:[1,0]
	v_mov_b32_e32 v76, v56
	v_mov_b32_e32 v77, v55
	v_pk_add_f32 v[32:33], v[32:33], v[34:35]
	v_pk_add_f32 v[34:35], v[44:45], v[46:47]
	v_pk_add_f32 v[44:45], v[74:75], v[76:77]
	v_pk_add_f32 v[32:33], v[32:33], v[34:35]
	v_pk_add_f32 v[34:35], v[44:45], v[44:45] op_sel:[0,1] op_sel_hi:[1,0]
	v_add_f32_e32 v1, 0, v32
	s_waitcnt vmcnt(4)
	v_pk_fma_f32 v[36:37], v[78:79], s[8:9], v[106:107] op_sel_hi:[1,0,1]
	v_pk_fma_f32 v[38:39], v[80:81], s[8:9], v[108:109] op_sel_hi:[1,0,1]
	v_add_f32_e32 v78, v52, v53
	v_add_f32_e32 v80, v50, v51
	v_mov_b32_e32 v95, v42
	v_mov_b32_e32 v79, v40
	v_mov_b32_e32 v81, v41
	v_mov_b32_e32 v35, v43
	v_add_f32_e32 v94, v1, v33
	v_pk_add_f32 v[46:47], v[78:79], v[80:81]
	v_pk_add_f32 v[32:33], v[94:95], v[34:35]
	v_pk_mov_b32 v[96:97], v[36:37], v[38:39] op_sel:[1,0]
	v_pk_add_f32 v[32:33], v[32:33], v[46:47]
	v_mov_b32_e32 v98, v36
	v_mov_b32_e32 v99, v39
	v_pk_add_f32 v[76:77], v[32:33], v[32:33] op_sel:[0,1] op_sel_hi:[1,0]
	s_waitcnt vmcnt(3)
	v_lshlrev_b32_e32 v32, 16, v90
	v_and_b32_e32 v33, 0xffff0000, v90
	v_lshlrev_b32_e32 v34, 16, v91
	v_and_b32_e32 v35, 0xffff0000, v91
	v_pk_add_f32 v[74:75], v[96:97], v[98:99]
	s_waitcnt vmcnt(2)
	v_pk_fma_f32 v[44:45], v[84:85], s[8:9], v[34:35] op_sel_hi:[1,0,1]
	v_pk_fma_f32 v[46:47], v[82:83], s[8:9], v[32:33] op_sel_hi:[1,0,1]
	s_waitcnt vmcnt(1)
	v_lshlrev_b32_e32 v34, 16, v92
	v_and_b32_e32 v35, 0xffff0000, v92
	v_lshlrev_b32_e32 v32, 16, v93
	v_and_b32_e32 v33, 0xffff0000, v93
	v_pk_add_f32 v[74:75], v[74:75], v[74:75] op_sel:[0,1] op_sel_hi:[1,0]
	s_waitcnt vmcnt(0)
	v_pk_fma_f32 v[32:33], v[88:89], s[8:9], v[32:33] op_sel_hi:[1,0,1]
	v_pk_fma_f32 v[34:35], v[86:87], s[8:9], v[34:35] op_sel_hi:[1,0,1]
	v_add_f32_e32 v78, v46, v47
	v_add_f32_e32 v80, v44, v45
	v_mov_b32_e32 v77, v34
	v_mov_b32_e32 v75, v35
	v_mov_b32_e32 v79, v32
	v_mov_b32_e32 v81, v33
	v_pk_add_f32 v[74:75], v[76:77], v[74:75]
	v_pk_add_f32 v[76:77], v[78:79], v[80:81]
	s_nop 0
	v_pk_add_f32 v[74:75], v[74:75], v[76:77]
	s_nop 0
	v_add_f32_e32 v1, v74, v75
	ds_bpermute_b32 v74, v66, v1
	s_waitcnt lgkmcnt(0)
	v_add_f32_e32 v1, v1, v74
	ds_bpermute_b32 v74, v67, v1
	s_waitcnt lgkmcnt(0)
	v_add_f32_e32 v1, v1, v74
	ds_bpermute_b32 v74, v68, v1
	s_waitcnt lgkmcnt(0)
	v_add_f32_e32 v1, v1, v74
	ds_bpermute_b32 v74, v69, v1
	s_waitcnt lgkmcnt(0)
	v_add_f32_e32 v1, v1, v74
	ds_bpermute_b32 v74, v70, v1
	s_waitcnt lgkmcnt(0)
	v_add_f32_e32 v1, v1, v74
	ds_bpermute_b32 v74, v71, v1
	s_waitcnt lgkmcnt(0)
; __device__ __forceinline__ void phase_ln(const float* res, const bf16_t* br, float* out, const float* gam, const float* bet, bf16_t* xb) {
;     ...
;         const float mu = wave_sum(s) * (1.0f / DM); float q = 0.f;
; #pragma unroll
;         for (int j = 0; j < 8; ++j) { v[j] = v[j] - mu; q += (v[j][0] * v[j][0] + v[j][1] * v[j][1]) + (v[j][2] * v[j][2] + v[j][3] * v[j][3]); }
;         const float rstd = 1.0f / sqrtf(wave_sum(q) * (1.0f / DM) + LN_EPS);
	v_add_f32_e32 v1, v1, v74
	v_fmamk_f32 v65, v1, 0xba000000, v65
	v_fmamk_f32 v61, v1, 0xba000000, v61
	v_fmamk_f32 v63, v1, 0xba000000, v63
	v_fmac_f32_e32 v64, 0xba000000, v1
	v_fmamk_f32 v59, v1, 0xba000000, v59
	v_fmac_f32_e32 v60, 0xba000000, v1
	v_mov_b32_e32 v76, v65
	v_mov_b32_e32 v77, v61
	v_fmac_f32_e32 v62, 0xba000000, v1
	v_fmac_f32_e32 v58, 0xba000000, v1
	v_mov_b32_e32 v74, v64
	v_mov_b32_e32 v75, v60
	v_pk_mul_f32 v[76:77], v[76:77], v[76:77]
	v_mov_b32_e32 v78, v63
	v_mov_b32_e32 v79, v59
	v_pk_fma_f32 v[74:75], v[74:75], v[74:75], v[76:77]
	v_mov_b32_e32 v76, v62
	v_mov_b32_e32 v77, v58
	v_pk_mul_f32 v[78:79], v[78:79], v[78:79]
	v_fmamk_f32 v57, v1, 0xba000000, v57
	v_pk_fma_f32 v[76:77], v[76:77], v[76:77], v[78:79]
	v_fmac_f32_e32 v56, 0xba000000, v1
	v_pk_add_f32 v[74:75], v[74:75], v[76:77]
	v_fmamk_f32 v55, v1, 0xba000000, v55
	v_fmac_f32_e32 v54, 0xba000000, v1
	v_pk_add_f32 v[74:75], v[74:75], v[74:75] op_sel_hi:[0,1]
	v_pk_mul_f32 v[76:77], v[54:55], v[54:55]
	v_pk_mul_f32 v[78:79], v[56:57], v[56:57]
	v_fmac_f32_e32 v52, 0xba000000, v1
	v_pk_mov_b32 v[80:81], v[78:79], v[76:77] op_sel:[1,0]
	v_mov_b32_e32 v79, v77
	v_fmamk_f32 v53, v1, 0xba000000, v53
	v_fmac_f32_e32 v50, 0xba000000, v1
	v_mul_f32_e32 v74, v52, v52
	v_pk_add_f32 v[76:77], v[80:81], v[78:79]
	v_fmamk_f32 v51, v1, 0xba000000, v51
	v_pk_fma_f32 v[78:79], v[52:53], v[52:53], v[74:75] op_sel_hi:[1,1,0]
	v_mul_f32_e32 v74, v50, v50
	v_pk_add_f32 v[76:77], v[76:77], v[76:77] op_sel_hi:[0,1]
	v_pk_fma_f32 v[80:81], v[50:51], v[50:51], v[74:75] op_sel_hi:[1,1,0]
	v_fmamk_f32 v41, v1, 0xba000000, v41
	v_fmac_f32_e32 v40, 0xba000000, v1
	v_fmamk_f32 v43, v1, 0xba000000, v43
	v_fmac_f32_e32 v42, 0xba000000, v1
	v_mul_f32_e32 v78, v42, v42
	v_mul_f32_e32 v80, v43, v43
	v_mul_f32_e32 v76, v40, v40
	v_mul_f32_e32 v74, v41, v41
	v_pk_add_f32 v[78:79], v[78:79], v[80:81]
	v_pk_add_f32 v[74:75], v[76:77], v[74:75]
	v_fmamk_f32 v37, v1, 0xba000000, v37
	v_pk_add_f32 v[74:75], v[78:79], v[74:75]
	v_fmac_f32_e32 v36, 0xba000000, v1
	v_fmamk_f32 v39, v1, 0xba000000, v39
	v_fmac_f32_e32 v38, 0xba000000, v1
	v_pk_add_f32 v[74:75], v[74:75], v[74:75] op_sel_hi:[0,1]
	v_pk_mul_f32 v[76:77], v[38:39], v[38:39]
	v_pk_mul_f32 v[78:79], v[36:37], v[36:37]
	v_fmac_f32_e32 v46, 0xba000000, v1
	v_pk_mov_b32 v[80:81], v[78:79], v[76:77] op_sel:[1,0]
	v_mov_b32_e32 v79, v77
	v_fmamk_f32 v47, v1, 0xba000000, v47
	v_fmac_f32_e32 v44, 0xba000000, v1
	v_mul_f32_e32 v74, v46, v46
	v_pk_add_f32 v[76:77], v[80:81], v[78:79]
	v_fmamk_f32 v45, v1, 0xba000000, v45
	v_pk_fma_f32 v[78:79], v[46:47], v[46:47], v[74:75] op_sel_hi:[1,1,0]
	v_mul_f32_e32 v74, v44, v44
	v_pk_add_f32 v[76:77], v[76:77], v[76:77] op_sel_hi:[0,1]
	v_pk_fma_f32 v[80:81], v[44:45], v[44:45], v[74:75] op_sel_hi:[1,1,0]
	v_fmamk_f32 v33, v1, 0xba000000, v33
	v_fmac_f32_e32 v32, 0xba000000, v1
	v_fmamk_f32 v35, v1, 0xba000000, v35
	v_fmac_f32_e32 v34, 0xba000000, v1
	v_mul_f32_e32 v78, v34, v34
	v_mul_f32_e32 v80, v35, v35
	v_mul_f32_e32 v76, v32, v32
	v_mul_f32_e32 v74, v33, v33
	v_pk_add_f32 v[82:83], v[78:79], v[80:81]
	v_pk_add_f32 v[84:85], v[76:77], v[74:75]
	v_pk_add_f32 v[82:83], v[82:83], v[84:85]
	s_nop 0
	v_add_f32_e32 v1, v82, v83
	ds_bpermute_b32 v82, v66, v1
	s_waitcnt lgkmcnt(0)
	v_add_f32_e32 v1, v1, v82
	ds_bpermute_b32 v82, v67, v1
	s_waitcnt lgkmcnt(0)
	v_add_f32_e32 v1, v1, v82
	ds_bpermute_b32 v82, v68, v1
	s_waitcnt lgkmcnt(0)
	v_add_f32_e32 v1, v1, v82
	ds_bpermute_b32 v82, v69, v1
	s_waitcnt lgkmcnt(0)
	v_add_f32_e32 v1, v1, v82
	ds_bpermute_b32 v82, v70, v1
	s_waitcnt lgkmcnt(0)
	v_add_f32_e32 v1, v1, v82
	ds_bpermute_b32 v82, v71, v1
	s_waitcnt lgkmcnt(0)
; __device__ __forceinline__ unsigned pk2(float lo, float hi) { unsigned r; asm("v_cvt_pk_bf16_f32 %0, %1, %2" : "=v"(r) : "v"(lo), "v"(hi)); return r; }
; __device__ __forceinline__ void phase_ln(const float* res, const bf16_t* br, float* out, const float* gam, const float* bet, bf16_t* xb) {
;     ...
;         const float rstd = 1.0f / sqrtf(wave_sum(q) * (1.0f / DM) + LN_EPS);
;         f32x4* orow = (f32x4*)(out + (size_t)row * DM) + lane;
; #pragma unroll
;         for (int j = 0; j < 8; ++j) { const f32x4 gv = *((const f32x4*)gam + 64 * j + lane), bv = *((const f32x4*)bet + 64 * j + lane);
;             const f32x4 y = v[j] * rstd * gv + bv; __builtin_nontemporal_store(y, orow + 64 * j);
;             if (xb) { u32x2 wv; wv.x = pk2(y[0], y[1]); wv.y = pk2(y[2], y[3]); __builtin_nontemporal_store(wv, (u32x2*)(xb + (size_t)row * DM) + 64 * j + lane); } }
	v_add_f32_e32 v1, v1, v82
	v_fmamk_f32 v1, v1, 0x3a000000, v72
	v_mul_f32_e32 v82, 0x4f800000, v1
	v_cmp_gt_f32_e32 vcc, s11, v1
	s_nop 1
	v_cndmask_b32_e32 v1, v1, v82, vcc
	v_sqrt_f32_e32 v82, v1
	s_nop 0
	v_add_u32_e32 v83, -1, v82
	v_fma_f32 v84, -v83, v82, v1
	v_cmp_ge_f32_e64 s[0:1], 0, v84
	v_add_u32_e32 v84, 1, v82
	s_nop 0
	v_cndmask_b32_e64 v83, v82, v83, s[0:1]
	v_fma_f32 v82, -v84, v82, v1
	v_cmp_lt_f32_e64 s[0:1], 0, v82
	s_nop 1
	v_cndmask_b32_e64 v82, v83, v84, s[0:1]
	v_mul_f32_e32 v83, 0x37800000, v82
	v_cndmask_b32_e32 v82, v82, v83, vcc
	v_cmp_class_f32_e32 vcc, v1, v73
	s_nop 1
	v_cndmask_b32_e32 v1, v82, v1, vcc
	v_div_scale_f32 v82, s[0:1], v1, v1, 1.0
	v_rcp_f32_e32 v83, v82
	s_nop 0
	v_fma_f32 v84, -v82, v83, 1.0
	v_fmac_f32_e32 v83, v84, v83
	v_div_scale_f32 v84, vcc, 1.0, v1, 1.0
	v_mul_f32_e32 v85, v84, v83
	v_fma_f32 v86, -v82, v85, v84
	v_fmac_f32_e32 v85, v86, v83
	v_fma_f32 v82, -v82, v85, v84
	v_div_fmas_f32 v82, v82, v83, v85
	v_div_fixup_f32 v82, v82, v1, 1.0
	v_lshl_add_u64 v[84:85], v[6:7], 0, v[48:49]
	v_lshl_add_u64 v[86:87], v[12:13], 0, v[30:31]
	v_lshrrev_b64 v[224:225], 5, v[30:31]
	v_lshl_add_u64 v[86:87], v[86:87], 0, v[224:225]
	v_pk_mul_f32 v[30:31], v[64:65], v[82:83] op_sel_hi:[1,0]
	v_pk_mul_f32 v[48:49], v[62:63], v[82:83] op_sel_hi:[1,0]
	v_pk_fma_f32 v[62:63], v[160:161], v[30:31], v[164:165]
	v_pk_fma_f32 v[64:65], v[162:163], v[48:49], v[166:167]
	global_store_dwordx4 v[84:85], v[62:65], off nt
	v_cvt_pk_bf16_f32 v30, v62, v63
	v_cvt_pk_bf16_f32 v31, v64, v65
	global_store_dwordx2 v[86:87], v[30:31], off
	v_pk_mul_f32 v[30:31], v[60:61], v[82:83] op_sel_hi:[1,0]
	v_pk_mul_f32 v[48:49], v[58:59], v[82:83] op_sel_hi:[1,0]
	v_pk_mul_f32 v[40:41], v[40:41], v[82:83] op_sel_hi:[1,0]
	v_pk_mul_f32 v[44:45], v[44:45], v[82:83] op_sel_hi:[1,0]
	v_pk_mul_f32 v[32:33], v[32:33], v[82:83] op_sel_hi:[1,0]
	v_pk_fma_f32 v[60:61], v[170:171], v[48:49], v[174:175]
	v_pk_fma_f32 v[58:59], v[168:169], v[30:31], v[172:173]
	global_store_dwordx4 v[84:85], v[58:61], off offset:1024 nt
	v_cvt_pk_bf16_f32 v30, v58, v59
	v_cvt_pk_bf16_f32 v31, v60, v61
	global_store_dwordx2 v[86:87], v[30:31], off offset:512
	v_pk_mul_f32 v[30:31], v[56:57], v[82:83] op_sel_hi:[1,0]
	v_pk_mul_f32 v[48:49], v[54:55], v[82:83] op_sel_hi:[1,0]
	v_pk_fma_f32 v[54:55], v[176:177], v[30:31], v[180:181]
	v_pk_fma_f32 v[56:57], v[178:179], v[48:49], v[182:183]
	global_store_dwordx4 v[84:85], v[54:57], off offset:2048 nt
	v_cvt_pk_bf16_f32 v30, v54, v55
	v_cvt_pk_bf16_f32 v31, v56, v57
	global_store_dwordx2 v[86:87], v[30:31], off offset:1024
	v_pk_mul_f32 v[30:31], v[52:53], v[82:83] op_sel_hi:[1,0]
	v_pk_mul_f32 v[48:49], v[50:51], v[82:83] op_sel_hi:[1,0]
	v_pk_fma_f32 v[50:51], v[186:187], v[48:49], v[190:191]
	v_pk_fma_f32 v[48:49], v[184:185], v[30:31], v[188:189]
	global_store_dwordx4 v[84:85], v[48:51], off offset:3072 nt
	v_cvt_pk_bf16_f32 v30, v48, v49
	v_cvt_pk_bf16_f32 v31, v50, v51
	global_store_dwordx2 v[86:87], v[30:31], off offset:1536
	v_add_co_u32_e32 v56, vcc, s10, v84
	v_pk_mul_f32 v[30:31], v[42:43], v[82:83] op_sel_hi:[1,0]
	s_nop 0
	v_addc_co_u32_e32 v57, vcc, 0, v85, vcc
	v_cmp_lt_i32_e32 vcc, s12, v0
	s_or_b64 s[6:7], vcc, s[6:7]
	v_pk_fma_f32 v[42:43], v[194:195], v[40:41], v[198:199]
	v_pk_fma_f32 v[40:41], v[192:193], v[30:31], v[196:197]
	global_store_dwordx4 v[56:57], v[40:43], off nt
	v_cvt_pk_bf16_f32 v30, v40, v41
	v_cvt_pk_bf16_f32 v31, v42, v43
	global_store_dwordx2 v[86:87], v[30:31], off offset:2048
	v_pk_mul_f32 v[30:31], v[36:37], v[82:83] op_sel_hi:[1,0]
	v_pk_mul_f32 v[36:37], v[38:39], v[82:83] op_sel_hi:[1,0]
	v_pk_fma_f32 v[38:39], v[202:203], v[36:37], v[206:207]
	v_pk_fma_f32 v[36:37], v[200:201], v[30:31], v[204:205]
	global_store_dwordx4 v[56:57], v[36:39], off offset:1024 nt
	v_cvt_pk_bf16_f32 v30, v36, v37
	v_cvt_pk_bf16_f32 v31, v38, v39
	global_store_dwordx2 v[86:87], v[30:31], off offset:2560
	v_pk_mul_f32 v[30:31], v[46:47], v[82:83] op_sel_hi:[1,0]
	v_pk_fma_f32 v[38:39], v[44:45], v[210:211], v[214:215]
	v_pk_fma_f32 v[36:37], v[30:31], v[208:209], v[212:213]
	global_store_dwordx4 v[56:57], v[36:39], off offset:2048 nt
	v_cvt_pk_bf16_f32 v30, v36, v37
	v_cvt_pk_bf16_f32 v31, v38, v39
	global_store_dwordx2 v[86:87], v[30:31], off offset:3072
	v_pk_mul_f32 v[30:31], v[34:35], v[82:83] op_sel_hi:[1,0]
	v_pk_fma_f32 v[32:33], v[32:33], v[218:219], v[222:223]
	v_pk_fma_f32 v[30:31], v[30:31], v[216:217], v[220:221]
	global_store_dwordx4 v[56:57], v[30:33], off offset:3072 nt
	s_nop 1
	v_cvt_pk_bf16_f32 v30, v30, v31
	v_cvt_pk_bf16_f32 v31, v32, v33
	global_store_dwordx2 v[86:87], v[30:31], off offset:3584
	s_andn2_b64 exec, exec, s[6:7]
	s_cbranch_execnz .LBB0_814

; #define PG8_STAGE(bufoff, gbase, voff) do { _Pragma("unroll") for (int _i = 0; _i < 2; ++_i) \
;         __builtin_amdgcn_global_load_lds((const unsigned*)((const char*)(gbase) + (voff)[_i]), (PG8_LAS unsigned*)(lds + (bufoff) + ldsw + _i * 8192), 16, 0, 0); } while (0)
; #define PG8_WAIT_V(n) asm volatile("s_waitcnt vmcnt(" #n ")" ::: "memory")
; #define PG8_BAR __builtin_amdgcn_s_barrier()
; template <class Epi, class Sched, bool ALIGN_EPI = false, bool SP2 = false>
; __device__ __forceinline__ void gemm_phase(PG8_LAS unsigned char* lds, const Gemm g, const Sched& S, const Epi& E) {
;     const int tid = threadIdx.x, wid = __builtin_amdgcn_readfirstlane(tid >> 6), lane = tid & 63, wr = wid >> 2, wc = wid & 3, fr = lane & 15, fq = lane >> 4;
;     const int K = g.K, nt = K / BK;
;     unsigned voffA[2], voffB[2];
; #pragma unroll
;     for (int i = 0; i < 2; ++i) { int R, C; stage_rc(tid * 16 + i * 8192, R, C); const int Rb = Epi::PERM ? ((R & ~31) + perm32(R & 31)) : R;
;         voffA[i] = (unsigned)(R * K + C) * 2u; voffB[i] = (unsigned)(Rb * K + C) * 2u; }
;     const size_t kstep = (size_t)(BK * 2);
;     const size_t hstep = (size_t)HALF * K * 2;
;     const size_t tstep = 2 * hstep;
;     const unsigned ldsw = (unsigned)wid * 1024u;
;     const int aoff = lds_byte(wr * 64 + fr, fq * 8), boff = lds_byte(wc * 32 + fr, fq * 8);
;     ...
;     const char* cA = (const char*)(cur.seg ? g.A2 : g.A) + (size_t)cur.pm * tstep; const char* cB = (const char*)(cur.seg ? g.Bt2 : g.Bt) + (size_t)cur.pn * tstep;
;     S.a_ready(cur);
;     if constexpr (SP2) {
;         PG8_STAGE(PG8_SB(0, 0), cB, voffB); PG8_STAGE(PG8_SB(0, 1), cB + hstep, voffB); PG8_STAGE(PG8_SA(0, 0), cA, voffA); PG8_STAGE(PG8_SA(0, 1), cA + hstep, voffA);
;         if (wr == 1) PG8_BAR;
;         PG8_WAIT_V(2); PG8_BAR;
;         PG8_STAGE(PG8_SB(1, 0), cB + kstep, voffB); PG8_STAGE(PG8_SA(1, 0), cA + kstep, voffA); PG8_STAGE(PG8_SB(1, 1), cB + hstep + kstep, voffB);
;         PG8_WAIT_V(6); PG8_BAR;
.LBB0_870:
	v_readlane_b32 s4, v246, 12
	s_cmp_lt_i32 s4, 10
	s_cselect_b64 s[22:23], -1, 0
	s_and_b64 s[0:1], s[22:23], s[0:1]
	s_andn2_b64 vcc, exec, s[0:1]
	v_readlane_b32 s5, v246, 13
	v_readlane_b32 s6, v246, 14
	v_readlane_b32 s7, v246, 15
	s_cbranch_vccnz .LBB0_917
	v_lshrrev_b32_e32 v238, 3, v144
	v_and_b32_e32 v239, 7, v144
	v_and_b32_e32 v240, 7, v238
	v_xor_b32_e32 v239, v239, v240
	v_lshlrev_b32_e32 v239, 4, v239
	v_mul_u32_u24_e32 v240, 0x1080, v238
	v_add_u32_e32 v240, v240, v239
	v_add_u32_e32 v241, 0x42000, v240
	v_and_b32_e32 v242, 31, v238
	v_bfe_u32 v243, v242, 2, 2
	v_lshlrev_b32_e32 v243, 3, v243
	v_lshrrev_b32_e32 v230, 4, v242
	v_lshl_or_b32 v243, v230, 2, v243
	v_and_b32_e32 v230, 3, v242
	v_or_b32_e32 v243, v243, v230
	v_and_b32_e32 v230, 32, v238
	v_or_b32_e32 v243, v243, v230
	v_lshl_or_b32 v238, v243, 12, v239
	v_add_u32_e32 v239, 0x40000, v238
	v_readlane_b32 s0, v246, 0
	v_readlane_b32 s1, v246, 1
	s_mov_b32 s2, s0
	s_cmpk_lt_i32 s0, 0x1580
	s_cselect_b64 s[0:1], -1, 0
	s_cmpk_gt_i32 s2, 0x157f
	v_readfirstlane_b32 s2, v144
	s_cbranch_scc1 .LBB0_873
	v_readlane_b32 s4, v246, 0
	s_ashr_i32 s3, s4, 31
	s_lshr_b32 s3, s3, 29
	s_add_i32 s3, s4, s3
	s_mov_b32 s6, s4
	s_ashr_i32 s4, s3, 3
	s_and_b32 s3, s3, -8
	v_readlane_b32 s5, v246, 1
	s_sub_i32 s3, s6, s3
	s_cmp_lt_i32 s3, 0
	s_movk_i32 s5, 0x2b1
	s_cselect_b32 s5, s5, 0x2b0
	s_mul_i32 s3, s3, s5
	s_add_i32 s3, s3, s4
	s_mul_hi_i32 s4, s3, 0x2fa0be83
	s_lshr_b32 s5, s4, 31
	s_ashr_i32 s4, s4, 6
	s_add_i32 s4, s4, s5
	s_lshl_b32 s5, s4, 3
	s_mulk_i32 s4, 0x158
	s_sub_i32 s3, s3, s4
	s_sext_i32_i16 s4, s3
	s_bfe_u32 s4, s4, 0x3001c
	s_add_i32 s4, s3, s4
	s_sext_i32_i16 s6, s4
	s_and_b32 s4, s4, 0xfff8
	s_sub_i32 s3, s3, s4
	s_sext_i32_i16 s3, s3
	s_add_i32 s14, s5, s3
	s_ashr_i32 s16, s6, 3
.LBB0_873:
	s_andn2_b64 vcc, exec, s[0:1]
	s_cbranch_vccnz .LBB0_917
	v_readlane_b32 s0, v246, 10
	v_readlane_b32 s1, v246, 11
	s_add_u32 s33, s0, 0x1c800000
	s_waitcnt lgkmcnt(0)
	v_lshrrev_b32_e32 v2, 1, v144
	v_lshrrev_b32_e32 v3, 5, v144
	s_addc_u32 s35, s1, 0
	v_and_b32_e32 v2, 24, v2
	v_and_b32_e32 v3, 4, v3
	v_bfe_u32 v4, v144, 2, 2
	s_add_u32 s56, s0, 0x3e00000
	v_lshlrev_b32_e32 v0, 4, v144
	v_and_b32_e32 v1, 32, v144
	s_waitcnt vmcnt(0)
	v_bfe_u32 v10, v144, 2, 4
	v_or3_b32 v2, v3, v4, v2
	v_lshrrev_b32_e32 v3, 3, v144
	s_movk_i32 s0, 0x70
	v_bitop3_b32 v8, v0, v1, 48 bitop3:0x6c
	v_and_b32_e32 v9, 64, v144
	v_and_or_b32 v4, v3, s0, v10
	s_movk_i32 s0, 0x60
	v_add_u32_e32 v11, 0x2000, v0
	v_or_b32_e32 v1, v8, v9
	v_and_or_b32 v3, v3, s0, v2
	v_lshrrev_b32_e32 v0, 7, v11
	s_movk_i32 s0, 0xf0
	v_lshl_or_b32 v148, v3, 12, v1
	v_mov_b32_e32 v148, v238
	v_and_or_b32 v3, v0, s0, v10
	s_movk_i32 s0, 0xe0
	s_addc_u32 s57, s1, 0
	v_and_or_b32 v0, v0, s0, v2
	s_lshr_b32 s0, s2, 6
	s_ashr_i32 s15, s14, 31
	s_ashr_i32 s17, s16, 31
	s_lshr_b32 s58, s2, 8
	s_lshl_b32 s59, s0, 10
	s_mul_i32 s4, s14, 0x108000
	s_mov_b32 s5, 0
	s_lshl_b64 s[6:7], s[16:17], 20
	s_add_u32 s20, s56, s6
	s_addc_u32 s21, s57, s7
	s_add_i32 s60, s59, 0
	s_add_i32 m0, s60, 0x10000
	v_lshl_or_b32 v152, v0, 12, v1
	v_mov_b32_e32 v152, v239
	global_load_lds_dwordx4 v148, s[20:21]
	s_add_i32 m0, s60, 0x12000
	s_add_u32 s6, s20, 0x80000
	global_load_lds_dwordx4 v152, s[20:21]
	s_addc_u32 s7, s21, 0
	s_add_i32 m0, s60, 0x14000
	v_lshl_or_b32 v146, v4, 12, v1
	v_mov_b32_e32 v146, v240
	global_load_lds_dwordx4 v148, s[6:7]
	s_add_i32 m0, s60, 0x16000
	s_add_u32 s18, s33, s4
	s_addc_u32 s19, s35, s5
	s_add_i32 s61, s60, 0x2000
	global_load_lds_dwordx4 v152, s[6:7]
	s_mov_b32 m0, s60
	s_add_u32 s4, s18, 0x84000
	v_lshl_or_b32 v150, v3, 12, v1
	v_mov_b32_e32 v150, v241
	global_load_lds_dwordx4 v146, s[18:19]
	s_mov_b32 m0, s61
	s_addc_u32 s5, s19, 0
	s_add_i32 s62, s60, 0x4000
	global_load_lds_dwordx4 v150, s[18:19]
	s_mov_b32 m0, s62
	s_add_i32 s63, s60, 0x6000
	global_load_lds_dwordx4 v146, s[4:5]
	s_mov_b32 m0, s63
	v_mov_b32_e32 v155, 0
	global_load_lds_dwordx4 v150, s[4:5]
	v_mov_b32_e32 v149, v155
	v_mov_b32_e32 v153, v155
	v_mov_b32_e32 v147, v155
	v_mov_b32_e32 v151, v155
	s_cmp_eq_u32 s58, 1
	s_mov_b32 s64, 0
	v_lshl_add_u64 v[6:7], s[20:21], 0, v[148:149]
	v_lshl_add_u64 v[4:5], s[20:21], 0, v[152:153]
	v_lshl_add_u64 v[0:1], s[18:19], 0, v[146:147]
	s_cselect_b64 s[24:25], -1, 0
	s_cmp_lg_u32 s58, 1
	v_lshl_add_u64 v[2:3], s[18:19], 0, v[150:151]
	s_cbranch_scc1 .LBB0_876
	s_barrier

; #define PG8_STAGE(bufoff, gbase, voff) do { _Pragma("unroll") for (int _i = 0; _i < 2; ++_i) \
;         __builtin_amdgcn_global_load_lds((const unsigned*)((const char*)(gbase) + (voff)[_i]), (PG8_LAS unsigned*)(lds + (bufoff) + ldsw + _i * 8192), 16, 0, 0); } while (0)
; #define PG8_LDA(dst, b, h) do { _Pragma("unroll") for (int m = 0; m < 4; ++m) _Pragma("unroll") for (int k = 0; k < 2; ++k) dst[m][k] = *(const PG8_LAS bf16x8*)(lds + PG8_SA(b, h) + aoff + m * 2048 + k * 1024); } while (0)
; #define PG8_LDB(dst, b, h) do { _Pragma("unroll") for (int n = 0; n < 2; ++n) _Pragma("unroll") for (int k = 0; k < 2; ++k) dst[n][k] = *(const PG8_LAS bf16x8*)(lds + PG8_SB(b, h) + boff + n * 2048 + k * 1024); } while (0)
; #define PG8_WAIT_V(n) asm volatile("s_waitcnt vmcnt(" #n ")" ::: "memory")
; #define PG8_WAIT_L(n) asm volatile("s_waitcnt lgkmcnt(" #n ")" ::: "memory")
; #define PG8_BAR __builtin_amdgcn_s_barrier()
; #define PG8_SCHED __builtin_amdgcn_sched_barrier(0)
; template <class Epi, class Sched, bool ALIGN_EPI = false, bool SP2 = false>
; __device__ __forceinline__ void gemm_phase(PG8_LAS unsigned char* lds, const Gemm g, const Sched& S, const Epi& E) {
;     ...
;         const bool has_next = S.next(ui + 1, nxt);
;         const char* nA = has_next ? (const char*)(nxt.seg ? g.A2 : g.A) + (size_t)nxt.pm * tstep : cA; const char* nB = has_next ? (const char*)(nxt.seg ? g.Bt2 : g.Bt) + (size_t)nxt.pn * tstep : cB;
;         for (int t = 0; t < nt; t += 2) {
;             const bool last = (t == nt - 2);
;             const char* a1 = cA + (size_t)(t + 1) * kstep;
;             const char* a2 = last ? nA : cA + (size_t)(t + 2) * kstep; const char* b2 = last ? nB : cB + (size_t)(t + 2) * kstep;
;             const char* a3 = a2 + kstep; const char* b3 = b2 + kstep;
;             if (last && has_next) S.a_ready(nxt);
;             if constexpr (SP2) {
;             PG8_LDB(B0, 0, 0); PG8_LDB(B1, 0, 1); PG8_SCHED; PG8_LDA(At, 0, 0); PG8_STAGE(PG8_SA(1, 1), a1 + hstep, voffA);
;             PG8_WAIT_V(8); PG8_WAIT_L(0); PG8_BAR; PG8_MMA(0, 0, At, B0); PG8_MMA(0, 1, At, B1); PG8_BAR; PG8_SCHED;
;     ...
;         for (int a = 0; a < 2; ++a)
; #pragma unroll
;             for (int b = 0; b < 2; ++b)
; #pragma unroll
;                 for (int m = 0; m < 4; ++m)
; #pragma unroll
;                     for (int n = 0; n < 2; ++n) acc[a][b][m][n] = (f32x4){0.f, 0.f, 0.f, 0.f};
.LBB0_881:
	s_ashr_i32 s49, s48, 31
	s_mul_i32 s36, s48, 0x108000
	s_mov_b32 s37, 0
	s_add_u32 s50, s33, s36
	s_addc_u32 s51, s35, s37
	s_and_b64 s[36:37], s[12:13], exec
	s_cselect_b32 s15, s51, s19
	s_cselect_b32 s17, s50, s18
	s_ashr_i32 s47, s46, 31
	s_lshl_b64 s[36:37], s[46:47], 20
	s_add_u32 s52, s56, s36
	s_addc_u32 s53, s57, s37
	s_and_b64 s[36:37], s[12:13], exec
	s_cselect_b32 s47, s53, s21
	s_cselect_b32 s49, s52, s20
	s_add_u32 s18, s18, 0x84080
	s_addc_u32 s19, s19, 0
	s_add_u32 s76, s20, 0x100
	v_mov_b32_e32 v120, 0
	s_addc_u32 s77, s21, 0
	s_mov_b32 s78, -2
	v_mov_b32_e32 v121, v120
	v_mov_b32_e32 v122, v120
	v_mov_b32_e32 v123, v120
	v_mov_b32_e32 v88, v120
	v_mov_b32_e32 v89, v120
	v_mov_b32_e32 v90, v120
	v_mov_b32_e32 v91, v120
	v_mov_b32_e32 v100, v120
	v_mov_b32_e32 v101, v120
	v_mov_b32_e32 v102, v120
	v_mov_b32_e32 v103, v120
	v_mov_b32_e32 v68, v120
	v_mov_b32_e32 v69, v120
	v_mov_b32_e32 v70, v120
	v_mov_b32_e32 v71, v120
	v_mov_b32_e32 v28, v120
	v_mov_b32_e32 v29, v120
	v_mov_b32_e32 v30, v120
	v_mov_b32_e32 v31, v120
	v_mov_b32_e32 v8, v120
	v_mov_b32_e32 v9, v120
	v_mov_b32_e32 v10, v120
	v_mov_b32_e32 v11, v120
	v_mov_b32_e32 v24, v120
	v_mov_b32_e32 v25, v120
	v_mov_b32_e32 v26, v120
	v_mov_b32_e32 v27, v120
	v_mov_b32_e32 v0, v120
	v_mov_b32_e32 v1, v120
	v_mov_b32_e32 v2, v120
	v_mov_b32_e32 v3, v120
	v_mov_b32_e32 v32, v120
	v_mov_b32_e32 v33, v120
	v_mov_b32_e32 v34, v120
	v_mov_b32_e32 v35, v120
	v_mov_b32_e32 v4, v120
	v_mov_b32_e32 v5, v120
	v_mov_b32_e32 v6, v120
	v_mov_b32_e32 v7, v120
	v_mov_b32_e32 v36, v120
	v_mov_b32_e32 v37, v120
	v_mov_b32_e32 v38, v120
	v_mov_b32_e32 v39, v120
	v_mov_b32_e32 v12, v120
	v_mov_b32_e32 v13, v120
	v_mov_b32_e32 v14, v120
	v_mov_b32_e32 v15, v120
	v_mov_b32_e32 v40, v120
	v_mov_b32_e32 v41, v120
	v_mov_b32_e32 v42, v120
	v_mov_b32_e32 v43, v120
	v_mov_b32_e32 v56, v120
	v_mov_b32_e32 v57, v120
	v_mov_b32_e32 v58, v120
	v_mov_b32_e32 v59, v120
	v_mov_b32_e32 v44, v120
	v_mov_b32_e32 v45, v120
	v_mov_b32_e32 v46, v120
	v_mov_b32_e32 v47, v120
	v_mov_b32_e32 v16, v120
	v_mov_b32_e32 v17, v120
	v_mov_b32_e32 v18, v120
	v_mov_b32_e32 v19, v120
	v_mov_b32_e32 v48, v120
	v_mov_b32_e32 v49, v120
	v_mov_b32_e32 v50, v120
	v_mov_b32_e32 v51, v120
	v_mov_b32_e32 v20, v120
	v_mov_b32_e32 v21, v120
	v_mov_b32_e32 v22, v120
	v_mov_b32_e32 v23, v120
	v_mov_b32_e32 v52, v120
	v_mov_b32_e32 v53, v120
	v_mov_b32_e32 v54, v120
	v_mov_b32_e32 v55, v120
	v_mov_b32_e32 v60, v120
	v_mov_b32_e32 v61, v120
	v_mov_b32_e32 v62, v120
	v_mov_b32_e32 v63, v120
	v_mov_b32_e32 v64, v120
	v_mov_b32_e32 v65, v120
	v_mov_b32_e32 v66, v120
	v_mov_b32_e32 v67, v120
	v_mov_b32_e32 v96, v120
	v_mov_b32_e32 v97, v120
	v_mov_b32_e32 v98, v120
	v_mov_b32_e32 v99, v120
	v_mov_b32_e32 v72, v120
	v_mov_b32_e32 v73, v120
	v_mov_b32_e32 v74, v120
	v_mov_b32_e32 v75, v120
	v_mov_b32_e32 v104, v120
	v_mov_b32_e32 v105, v120
	v_mov_b32_e32 v106, v120
	v_mov_b32_e32 v107, v120
	v_mov_b32_e32 v76, v120
	v_mov_b32_e32 v77, v120
	v_mov_b32_e32 v78, v120
	v_mov_b32_e32 v79, v120
	v_mov_b32_e32 v108, v120
	v_mov_b32_e32 v109, v120
	v_mov_b32_e32 v110, v120
	v_mov_b32_e32 v111, v120
	v_mov_b32_e32 v92, v120
	v_mov_b32_e32 v93, v120
	v_mov_b32_e32 v94, v120
	v_mov_b32_e32 v95, v120
	v_mov_b32_e32 v124, v120
	v_mov_b32_e32 v125, v120
	v_mov_b32_e32 v126, v120
	v_mov_b32_e32 v127, v120
	v_mov_b32_e32 v80, v120
	v_mov_b32_e32 v81, v120
	v_mov_b32_e32 v82, v120
	v_mov_b32_e32 v83, v120
	v_mov_b32_e32 v112, v120
	v_mov_b32_e32 v113, v120
	v_mov_b32_e32 v114, v120
	v_mov_b32_e32 v115, v120
	v_mov_b32_e32 v84, v120
	v_mov_b32_e32 v85, v120
	v_mov_b32_e32 v86, v120
	v_mov_b32_e32 v87, v120
	v_mov_b32_e32 v116, v120
	v_mov_b32_e32 v117, v120
	v_mov_b32_e32 v118, v120
	v_mov_b32_e32 v119, v120
.LBB0_882:
	ds_read_b128 v[128:131], v187
	ds_read_b128 v[132:135], v188
	ds_read_b128 v[136:139], v187 offset:2048
	ds_read_b128 v[140:143], v188 offset:2048
	ds_read_b128 v[168:171], v187 offset:16384
	ds_read_b128 v[172:175], v188 offset:16384
	ds_read_b128 v[176:179], v187 offset:18432
	ds_read_b128 v[194:197], v188 offset:18432
	s_add_u32 s20, s18, 0xfff7c080
	s_addc_u32 s21, s19, -1
	s_cmp_eq_u32 s78, 28
	s_cselect_b32 s55, s15, s21
	s_cselect_b32 s54, s17, s20
	s_cselect_b32 s21, s47, s77
	s_cselect_b32 s20, s49, s76
	v_lshl_add_u64 v[180:181], s[18:19], 0, v[160:161]
	s_add_i32 m0, s60, 0xc000
	ds_read_b128 v[198:201], v189
	ds_read_b128 v[202:205], v242
	ds_read_b128 v[206:209], v189 offset:2048
	ds_read_b128 v[210:213], v242 offset:2048
	ds_read_b128 v[214:217], v189 offset:4096
	ds_read_b128 v[218:221], v242 offset:4096
	ds_read_b128 v[222:225], v189 offset:6144
	ds_read_b128 v[226:229], v242 offset:6144
	global_load_lds_dwordx4 v[180:181], off
	v_lshl_add_u64 v[180:181], s[18:19], 0, v[162:163]
	s_add_i32 m0, s60, 0xe000
	s_nop 0
	global_load_lds_dwordx4 v[180:181], off
	s_waitcnt vmcnt(8)
	s_waitcnt lgkmcnt(0)
	s_barrier
; #define PG8_STAGE(bufoff, gbase, voff) do { _Pragma("unroll") for (int _i = 0; _i < 2; ++_i) \
;         __builtin_amdgcn_global_load_lds((const unsigned*)((const char*)(gbase) + (voff)[_i]), (PG8_LAS unsigned*)(lds + (bufoff) + ldsw + _i * 8192), 16, 0, 0); } while (0)
; #define PG8_LDA(dst, b, h) do { _Pragma("unroll") for (int m = 0; m < 4; ++m) _Pragma("unroll") for (int k = 0; k < 2; ++k) dst[m][k] = *(const PG8_LAS bf16x8*)(lds + PG8_SA(b, h) + aoff + m * 2048 + k * 1024); } while (0)
; #define PG8_MMA(ai, bj, At, Bt) do { __builtin_amdgcn_s_setprio(1); _Pragma("unroll") for (int m = 0; m < 4; ++m) _Pragma("unroll") for (int n = 0; n < 2; ++n) _Pragma("unroll") for (int k = 0; k < 2; ++k) \
;         acc[ai][bj][m][n] = __builtin_amdgcn_mfma_f32_16x16x32_bf16(Bt[n][k], At[m][k], acc[ai][bj][m][n], 0, 0, 0); __builtin_amdgcn_s_setprio(0); } while (0)
; #define PG8_WAIT_V(n) asm volatile("s_waitcnt vmcnt(" #n ")" ::: "memory")
; #define PG8_WAIT_L(n) asm volatile("s_waitcnt lgkmcnt(" #n ")" ::: "memory")
; #define PG8_BAR __builtin_amdgcn_s_barrier()
; #define PG8_SCHED __builtin_amdgcn_sched_barrier(0)
; template <class Epi, class Sched, bool ALIGN_EPI = false, bool SP2 = false>
; __device__ __forceinline__ void gemm_phase(PG8_LAS unsigned char* lds, const Gemm g, const Sched& S, const Epi& E) {
;     ...
;             PG8_WAIT_V(8); PG8_WAIT_L(0); PG8_BAR; PG8_MMA(0, 0, At, B0); PG8_MMA(0, 1, At, B1); PG8_BAR; PG8_SCHED;
;             PG8_LDA(At, 0, 1); PG8_STAGE(PG8_SB(0, 0), b2, voffB); PG8_STAGE(PG8_SB(0, 1), b2 + hstep, voffB); PG8_STAGE(PG8_SA(0, 0), a2, voffA);
;             PG8_WAIT_V(8); PG8_WAIT_L(0); PG8_BAR; PG8_MMA(1, 0, At, B0); PG8_MMA(1, 1, At, B1); PG8_BAR; PG8_SCHED;
	s_setprio 1
	s_waitcnt lgkmcnt(0)
	v_mfma_f32_16x16x32_bf16 v[120:123], v[128:131], v[198:201], v[120:123]
	v_mfma_f32_16x16x32_bf16 v[88:91], v[136:139], v[198:201], v[88:91]
	v_mfma_f32_16x16x32_bf16 v[116:119], v[128:131], v[206:209], v[116:119]
	v_mfma_f32_16x16x32_bf16 v[84:87], v[136:139], v[206:209], v[84:87]
	v_mfma_f32_16x16x32_bf16 v[112:115], v[128:131], v[214:217], v[112:115]
	v_mfma_f32_16x16x32_bf16 v[80:83], v[136:139], v[214:217], v[80:83]
	v_mfma_f32_16x16x32_bf16 v[100:103], v[128:131], v[222:225], v[100:103]
	v_mfma_f32_16x16x32_bf16 v[68:71], v[136:139], v[222:225], v[68:71]
	v_mfma_f32_16x16x32_bf16 v[120:123], v[132:135], v[202:205], v[120:123]
	v_mfma_f32_16x16x32_bf16 v[88:91], v[140:143], v[202:205], v[88:91]
	v_mfma_f32_16x16x32_bf16 v[116:119], v[132:135], v[210:213], v[116:119]
	v_mfma_f32_16x16x32_bf16 v[84:87], v[140:143], v[210:213], v[84:87]
	v_mfma_f32_16x16x32_bf16 v[112:115], v[132:135], v[218:221], v[112:115]
	v_mfma_f32_16x16x32_bf16 v[80:83], v[140:143], v[218:221], v[80:83]
	v_mfma_f32_16x16x32_bf16 v[100:103], v[132:135], v[226:229], v[100:103]
	v_mfma_f32_16x16x32_bf16 v[68:71], v[140:143], v[226:229], v[68:71]
	s_setprio 0
	s_setprio 1
	v_mfma_f32_16x16x32_bf16 v[124:127], v[168:171], v[198:201], v[124:127]
	v_mfma_f32_16x16x32_bf16 v[92:95], v[176:179], v[198:201], v[92:95]
	v_mfma_f32_16x16x32_bf16 v[108:111], v[168:171], v[206:209], v[108:111]
	v_mfma_f32_16x16x32_bf16 v[76:79], v[176:179], v[206:209], v[76:79]
	v_mfma_f32_16x16x32_bf16 v[104:107], v[168:171], v[214:217], v[104:107]
	v_mfma_f32_16x16x32_bf16 v[72:75], v[176:179], v[214:217], v[72:75]
	v_mfma_f32_16x16x32_bf16 v[96:99], v[168:171], v[222:225], v[96:99]
	v_mfma_f32_16x16x32_bf16 v[64:67], v[176:179], v[222:225], v[64:67]
	v_mfma_f32_16x16x32_bf16 v[124:127], v[172:175], v[202:205], v[124:127]
	v_mfma_f32_16x16x32_bf16 v[92:95], v[194:197], v[202:205], v[92:95]
	v_mfma_f32_16x16x32_bf16 v[108:111], v[172:175], v[210:213], v[108:111]
	v_mfma_f32_16x16x32_bf16 v[76:79], v[194:197], v[210:213], v[76:79]
	v_mfma_f32_16x16x32_bf16 v[104:107], v[172:175], v[218:221], v[104:107]
	v_mfma_f32_16x16x32_bf16 v[72:75], v[194:197], v[218:221], v[72:75]
	v_mfma_f32_16x16x32_bf16 v[96:99], v[172:175], v[226:229], v[96:99]
	v_mfma_f32_16x16x32_bf16 v[64:67], v[194:197], v[226:229], v[64:67]
	s_setprio 0
	s_barrier
	s_add_i32 s36, s72, s59
	v_lshl_add_u64 v[180:181], s[20:21], 0, v[148:149]
	s_mov_b32 m0, s36
	ds_read_b128 v[198:201], v189 offset:16384
	ds_read_b128 v[202:205], v242 offset:16384
	ds_read_b128 v[206:209], v189 offset:18432
	ds_read_b128 v[210:213], v242 offset:18432
	ds_read_b128 v[214:217], v189 offset:20480
	ds_read_b128 v[218:221], v242 offset:20480
	ds_read_b128 v[222:225], v189 offset:22528
	ds_read_b128 v[226:229], v242 offset:22528
	global_load_lds_dwordx4 v[180:181], off
	s_add_i32 m0, s36, 0x2000
	s_add_u32 s36, s20, 0x80000
	v_lshl_add_u64 v[230:231], s[20:21], 0, v[152:153]
	s_addc_u32 s37, s21, 0
	s_add_i32 s79, s73, s59
	global_load_lds_dwordx4 v[230:231], off
	v_lshl_add_u64 v[232:233], s[36:37], 0, v[148:149]
	s_mov_b32 m0, s79
	v_lshl_add_u64 v[234:235], s[54:55], 0, v[150:151]
	global_load_lds_dwordx4 v[232:233], off
	v_lshl_add_u64 v[232:233], s[36:37], 0, v[152:153]
	s_add_i32 m0, s79, 0x2000
	s_nop 0
	global_load_lds_dwordx4 v[232:233], off
	v_lshl_add_u64 v[232:233], s[54:55], 0, v[146:147]
	s_mov_b32 m0, s60
	s_nop 0
	global_load_lds_dwordx4 v[232:233], off
	s_mov_b32 m0, s61
	s_nop 0
	global_load_lds_dwordx4 v[234:235], off
	s_waitcnt vmcnt(8)
	s_waitcnt lgkmcnt(0)
	s_barrier
	s_setprio 1
	s_waitcnt lgkmcnt(0)
	v_mfma_f32_16x16x32_bf16 v[60:63], v[128:131], v[198:201], v[60:63]
	v_mfma_f32_16x16x32_bf16 v[28:31], v[136:139], v[198:201], v[28:31]
	v_mfma_f32_16x16x32_bf16 v[52:55], v[128:131], v[206:209], v[52:55]
	v_mfma_f32_16x16x32_bf16 v[20:23], v[136:139], v[206:209], v[20:23]
	v_mfma_f32_16x16x32_bf16 v[48:51], v[128:131], v[214:217], v[48:51]
	v_mfma_f32_16x16x32_bf16 v[16:19], v[136:139], v[214:217], v[16:19]
	v_mfma_f32_16x16x32_bf16 v[44:47], v[128:131], v[222:225], v[44:47]
	v_mfma_f32_16x16x32_bf16 v[8:11], v[136:139], v[222:225], v[8:11]
	v_mfma_f32_16x16x32_bf16 v[60:63], v[132:135], v[202:205], v[60:63]
	v_mfma_f32_16x16x32_bf16 v[28:31], v[140:143], v[202:205], v[28:31]
	v_mfma_f32_16x16x32_bf16 v[52:55], v[132:135], v[210:213], v[52:55]
	v_mfma_f32_16x16x32_bf16 v[20:23], v[140:143], v[210:213], v[20:23]
	v_mfma_f32_16x16x32_bf16 v[48:51], v[132:135], v[218:221], v[48:51]
	v_mfma_f32_16x16x32_bf16 v[16:19], v[140:143], v[218:221], v[16:19]
	v_mfma_f32_16x16x32_bf16 v[44:47], v[132:135], v[226:229], v[44:47]
	v_mfma_f32_16x16x32_bf16 v[8:11], v[140:143], v[226:229], v[8:11]
	s_setprio 0
	s_setprio 1
	v_mfma_f32_16x16x32_bf16 v[56:59], v[168:171], v[198:201], v[56:59]
	v_mfma_f32_16x16x32_bf16 v[24:27], v[176:179], v[198:201], v[24:27]
	v_mfma_f32_16x16x32_bf16 v[40:43], v[168:171], v[206:209], v[40:43]
	v_mfma_f32_16x16x32_bf16 v[12:15], v[176:179], v[206:209], v[12:15]
	v_mfma_f32_16x16x32_bf16 v[36:39], v[168:171], v[214:217], v[36:39]
	v_mfma_f32_16x16x32_bf16 v[4:7], v[176:179], v[214:217], v[4:7]
	v_mfma_f32_16x16x32_bf16 v[32:35], v[168:171], v[222:225], v[32:35]
	v_mfma_f32_16x16x32_bf16 v[0:3], v[176:179], v[222:225], v[0:3]
	v_mfma_f32_16x16x32_bf16 v[56:59], v[172:175], v[202:205], v[56:59]
	v_mfma_f32_16x16x32_bf16 v[24:27], v[194:197], v[202:205], v[24:27]
	v_mfma_f32_16x16x32_bf16 v[40:43], v[172:175], v[210:213], v[40:43]
	v_mfma_f32_16x16x32_bf16 v[12:15], v[194:197], v[210:213], v[12:15]
	v_mfma_f32_16x16x32_bf16 v[36:39], v[172:175], v[218:221], v[36:39]
	v_mfma_f32_16x16x32_bf16 v[4:7], v[194:197], v[218:221], v[4:7]
	v_mfma_f32_16x16x32_bf16 v[32:35], v[172:175], v[226:229], v[32:35]
	v_mfma_f32_16x16x32_bf16 v[0:3], v[194:197], v[226:229], v[0:3]
	s_setprio 0
	s_barrier
; #define PG8_STAGE(bufoff, gbase, voff) do { _Pragma("unroll") for (int _i = 0; _i < 2; ++_i) \
;         __builtin_amdgcn_global_load_lds((const unsigned*)((const char*)(gbase) + (voff)[_i]), (PG8_LAS unsigned*)(lds + (bufoff) + ldsw + _i * 8192), 16, 0, 0); } while (0)
; #define PG8_LDA(dst, b, h) do { _Pragma("unroll") for (int m = 0; m < 4; ++m) _Pragma("unroll") for (int k = 0; k < 2; ++k) dst[m][k] = *(const PG8_LAS bf16x8*)(lds + PG8_SA(b, h) + aoff + m * 2048 + k * 1024); } while (0)
; #define PG8_LDB(dst, b, h) do { _Pragma("unroll") for (int n = 0; n < 2; ++n) _Pragma("unroll") for (int k = 0; k < 2; ++k) dst[n][k] = *(const PG8_LAS bf16x8*)(lds + PG8_SB(b, h) + boff + n * 2048 + k * 1024); } while (0)
; #define PG8_MMA(ai, bj, At, Bt) do { __builtin_amdgcn_s_setprio(1); _Pragma("unroll") for (int m = 0; m < 4; ++m) _Pragma("unroll") for (int n = 0; n < 2; ++n) _Pragma("unroll") for (int k = 0; k < 2; ++k) \
;         acc[ai][bj][m][n] = __builtin_amdgcn_mfma_f32_16x16x32_bf16(Bt[n][k], At[m][k], acc[ai][bj][m][n], 0, 0, 0); __builtin_amdgcn_s_setprio(0); } while (0)
; #define PG8_WAIT_V(n) asm volatile("s_waitcnt vmcnt(" #n ")" ::: "memory")
; #define PG8_WAIT_L(n) asm volatile("s_waitcnt lgkmcnt(" #n ")" ::: "memory")
; #define PG8_BAR __builtin_amdgcn_s_barrier()
; #define PG8_SCHED __builtin_amdgcn_sched_barrier(0)
; template <class Epi, class Sched, bool ALIGN_EPI = false, bool SP2 = false>
; __device__ __forceinline__ void gemm_phase(PG8_LAS unsigned char* lds, const Gemm g, const Sched& S, const Epi& E) {
;     ...
;             PG8_LDB(B0, 1, 0); PG8_LDB(B1, 1, 1); PG8_SCHED; PG8_LDA(At, 1, 0); PG8_STAGE(PG8_SA(0, 1), a2 + hstep, voffA);
;             PG8_WAIT_V(8); PG8_WAIT_L(0); PG8_BAR; PG8_MMA(0, 0, At, B0); PG8_MMA(0, 1, At, B1); PG8_BAR; PG8_SCHED;
	s_add_i32 s79, 0, 0x18000
	s_add_i32 s80, 0, 0x1c000
	v_add_u32_e32 v140, s79, v182
	v_add_u32_e32 v154, s80, v182
	ds_read_b128 v[128:131], v187 offset:32768
	ds_read_b128 v[132:135], v188 offset:32768
	ds_read_b128 v[136:139], v187 offset:34816
	ds_read_b128 v[140:143], v188 offset:34816
	ds_read_b128 v[168:171], v187 offset:49152
	ds_read_b128 v[172:175], v188 offset:49152
	ds_read_b128 v[176:179], v187 offset:51200
	ds_read_b128 v[194:197], v188 offset:51200
	s_add_u32 s36, s54, 0x84000
	s_addc_u32 s37, s55, 0
	s_mov_b32 m0, s62
	v_lshl_add_u64 v[236:237], s[36:37], 0, v[146:147]
	ds_read_b128 v[198:201], v189 offset:32768
	ds_read_b128 v[202:205], v242 offset:32768
	ds_read_b128 v[206:209], v189 offset:34816
	ds_read_b128 v[210:213], v242 offset:34816
	ds_read_b128 v[214:217], v189 offset:36864
	ds_read_b128 v[218:221], v242 offset:36864
	ds_read_b128 v[222:225], v189 offset:38912
	ds_read_b128 v[226:229], v242 offset:38912
	global_load_lds_dwordx4 v[236:237], off
	v_lshl_add_u64 v[236:237], s[36:37], 0, v[150:151]
	s_mov_b32 m0, s63
	s_nop 0
	global_load_lds_dwordx4 v[236:237], off
	s_waitcnt vmcnt(8)
	s_waitcnt lgkmcnt(0)
	s_barrier
	s_setprio 1
	s_waitcnt lgkmcnt(0)
	v_mfma_f32_16x16x32_bf16 v[120:123], v[128:131], v[198:201], v[120:123]
	v_mfma_f32_16x16x32_bf16 v[88:91], v[136:139], v[198:201], v[88:91]
	v_mfma_f32_16x16x32_bf16 v[116:119], v[128:131], v[206:209], v[116:119]
	v_mfma_f32_16x16x32_bf16 v[84:87], v[136:139], v[206:209], v[84:87]
	v_mfma_f32_16x16x32_bf16 v[112:115], v[128:131], v[214:217], v[112:115]
	v_mfma_f32_16x16x32_bf16 v[80:83], v[136:139], v[214:217], v[80:83]
	v_mfma_f32_16x16x32_bf16 v[100:103], v[128:131], v[222:225], v[100:103]
	v_mfma_f32_16x16x32_bf16 v[68:71], v[136:139], v[222:225], v[68:71]
	v_mfma_f32_16x16x32_bf16 v[120:123], v[132:135], v[202:205], v[120:123]
	v_mfma_f32_16x16x32_bf16 v[88:91], v[140:143], v[202:205], v[88:91]
	v_mfma_f32_16x16x32_bf16 v[116:119], v[132:135], v[210:213], v[116:119]
	v_mfma_f32_16x16x32_bf16 v[84:87], v[140:143], v[210:213], v[84:87]
	v_mfma_f32_16x16x32_bf16 v[112:115], v[132:135], v[218:221], v[112:115]
	v_mfma_f32_16x16x32_bf16 v[80:83], v[140:143], v[218:221], v[80:83]
	v_mfma_f32_16x16x32_bf16 v[100:103], v[132:135], v[226:229], v[100:103]
	v_mfma_f32_16x16x32_bf16 v[68:71], v[140:143], v[226:229], v[68:71]
	s_setprio 0
	s_setprio 1
	v_mfma_f32_16x16x32_bf16 v[124:127], v[168:171], v[198:201], v[124:127]
	v_mfma_f32_16x16x32_bf16 v[92:95], v[176:179], v[198:201], v[92:95]
	v_mfma_f32_16x16x32_bf16 v[108:111], v[168:171], v[206:209], v[108:111]
	v_mfma_f32_16x16x32_bf16 v[76:79], v[176:179], v[206:209], v[76:79]
	v_mfma_f32_16x16x32_bf16 v[104:107], v[168:171], v[214:217], v[104:107]
	v_mfma_f32_16x16x32_bf16 v[72:75], v[176:179], v[214:217], v[72:75]
	v_mfma_f32_16x16x32_bf16 v[96:99], v[168:171], v[222:225], v[96:99]
	v_mfma_f32_16x16x32_bf16 v[64:67], v[176:179], v[222:225], v[64:67]
	v_mfma_f32_16x16x32_bf16 v[124:127], v[172:175], v[202:205], v[124:127]
	v_mfma_f32_16x16x32_bf16 v[92:95], v[194:197], v[202:205], v[92:95]
	v_mfma_f32_16x16x32_bf16 v[108:111], v[172:175], v[210:213], v[108:111]
	v_mfma_f32_16x16x32_bf16 v[76:79], v[194:197], v[210:213], v[76:79]
	v_mfma_f32_16x16x32_bf16 v[104:107], v[172:175], v[218:221], v[104:107]
	v_mfma_f32_16x16x32_bf16 v[72:75], v[194:197], v[218:221], v[72:75]
	v_mfma_f32_16x16x32_bf16 v[96:99], v[172:175], v[226:229], v[96:99]
	v_mfma_f32_16x16x32_bf16 v[64:67], v[194:197], v[226:229], v[64:67]
	s_setprio 0
	s_barrier
; #define PG8_STAGE(bufoff, gbase, voff) do { _Pragma("unroll") for (int _i = 0; _i < 2; ++_i) \
;         __builtin_amdgcn_global_load_lds((const unsigned*)((const char*)(gbase) + (voff)[_i]), (PG8_LAS unsigned*)(lds + (bufoff) + ldsw + _i * 8192), 16, 0, 0); } while (0)
; #define PG8_LDA(dst, b, h) do { _Pragma("unroll") for (int m = 0; m < 4; ++m) _Pragma("unroll") for (int k = 0; k < 2; ++k) dst[m][k] = *(const PG8_LAS bf16x8*)(lds + PG8_SA(b, h) + aoff + m * 2048 + k * 1024); } while (0)
; #define PG8_MMA(ai, bj, At, Bt) do { __builtin_amdgcn_s_setprio(1); _Pragma("unroll") for (int m = 0; m < 4; ++m) _Pragma("unroll") for (int n = 0; n < 2; ++n) _Pragma("unroll") for (int k = 0; k < 2; ++k) \
;         acc[ai][bj][m][n] = __builtin_amdgcn_mfma_f32_16x16x32_bf16(Bt[n][k], At[m][k], acc[ai][bj][m][n], 0, 0, 0); __builtin_amdgcn_s_setprio(0); } while (0)
; #define PG8_WAIT_V(n) asm volatile("s_waitcnt vmcnt(" #n ")" ::: "memory")
; #define PG8_WAIT_L(n) asm volatile("s_waitcnt lgkmcnt(" #n ")" ::: "memory")
; #define PG8_BAR __builtin_amdgcn_s_barrier()
; #define PG8_SCHED __builtin_amdgcn_sched_barrier(0)
; template <class Epi, class Sched, bool ALIGN_EPI = false, bool SP2 = false>
; __device__ __forceinline__ void gemm_phase(PG8_LAS unsigned char* lds, const Gemm g, const Sched& S, const Epi& E) {
;     ...
;         for (int t = 0; t < nt; t += 2) {
;     ...
;             PG8_LDA(At, 1, 1); PG8_STAGE(PG8_SB(1, 0), b3, voffB); PG8_STAGE(PG8_SB(1, 1), b3 + hstep, voffB); PG8_STAGE(PG8_SA(1, 0), a3, voffA);
;             PG8_WAIT_V(8); PG8_WAIT_L(0); PG8_BAR; PG8_MMA(1, 0, At, B0); PG8_MMA(1, 1, At, B1); PG8_BAR; PG8_SCHED;
	s_add_i32 s36, s79, s59
	v_lshl_add_u64 v[180:181], v[180:181], 0, s[28:29]
	s_mov_b32 m0, s36
	ds_read_b128 v[198:201], v189 offset:49152
	ds_read_b128 v[202:205], v242 offset:49152
	ds_read_b128 v[206:209], v189 offset:51200
	ds_read_b128 v[210:213], v242 offset:51200
	ds_read_b128 v[214:217], v189 offset:53248
	ds_read_b128 v[218:221], v242 offset:53248
	ds_read_b128 v[222:225], v189 offset:55296
	ds_read_b128 v[226:229], v242 offset:55296
	global_load_lds_dwordx4 v[180:181], off
	s_add_i32 m0, s36, 0x2000
	s_add_u32 s20, s20, 0x80080
	v_lshl_add_u64 v[180:181], v[230:231], 0, s[28:29]
	s_addc_u32 s21, s21, 0
	s_add_i32 s36, s80, s59
	global_load_lds_dwordx4 v[180:181], off
	v_lshl_add_u64 v[180:181], s[20:21], 0, v[148:149]
	s_mov_b32 m0, s36
	s_nop 0
	global_load_lds_dwordx4 v[180:181], off
	v_lshl_add_u64 v[180:181], s[20:21], 0, v[152:153]
	s_add_i32 m0, s36, 0x2000
	s_nop 0
	global_load_lds_dwordx4 v[180:181], off
	v_lshl_add_u64 v[180:181], v[232:233], 0, s[28:29]
	s_mov_b32 m0, s67
	s_nop 0
	global_load_lds_dwordx4 v[180:181], off
	v_lshl_add_u64 v[180:181], v[234:235], 0, s[28:29]
	s_mov_b32 m0, s68
	s_nop 0
	global_load_lds_dwordx4 v[180:181], off
	s_waitcnt vmcnt(8)
	s_waitcnt lgkmcnt(0)
	s_barrier
	s_setprio 1
	s_waitcnt lgkmcnt(0)
	v_mfma_f32_16x16x32_bf16 v[60:63], v[128:131], v[198:201], v[60:63]
	v_mfma_f32_16x16x32_bf16 v[28:31], v[136:139], v[198:201], v[28:31]
	v_mfma_f32_16x16x32_bf16 v[52:55], v[128:131], v[206:209], v[52:55]
	v_mfma_f32_16x16x32_bf16 v[20:23], v[136:139], v[206:209], v[20:23]
	v_mfma_f32_16x16x32_bf16 v[48:51], v[128:131], v[214:217], v[48:51]
	v_mfma_f32_16x16x32_bf16 v[16:19], v[136:139], v[214:217], v[16:19]
	v_mfma_f32_16x16x32_bf16 v[44:47], v[128:131], v[222:225], v[44:47]
	v_mfma_f32_16x16x32_bf16 v[8:11], v[136:139], v[222:225], v[8:11]
	v_mfma_f32_16x16x32_bf16 v[60:63], v[132:135], v[202:205], v[60:63]
	v_mfma_f32_16x16x32_bf16 v[28:31], v[140:143], v[202:205], v[28:31]
	v_mfma_f32_16x16x32_bf16 v[52:55], v[132:135], v[210:213], v[52:55]
	v_mfma_f32_16x16x32_bf16 v[20:23], v[140:143], v[210:213], v[20:23]
	v_mfma_f32_16x16x32_bf16 v[48:51], v[132:135], v[218:221], v[48:51]
	v_mfma_f32_16x16x32_bf16 v[16:19], v[140:143], v[218:221], v[16:19]
	v_mfma_f32_16x16x32_bf16 v[44:47], v[132:135], v[226:229], v[44:47]
	v_mfma_f32_16x16x32_bf16 v[8:11], v[140:143], v[226:229], v[8:11]
	s_setprio 0
	s_setprio 1
	v_mfma_f32_16x16x32_bf16 v[56:59], v[168:171], v[198:201], v[56:59]
	v_mfma_f32_16x16x32_bf16 v[24:27], v[176:179], v[198:201], v[24:27]
	v_mfma_f32_16x16x32_bf16 v[40:43], v[168:171], v[206:209], v[40:43]
	v_mfma_f32_16x16x32_bf16 v[12:15], v[176:179], v[206:209], v[12:15]
	v_mfma_f32_16x16x32_bf16 v[36:39], v[168:171], v[214:217], v[36:39]
	v_mfma_f32_16x16x32_bf16 v[4:7], v[176:179], v[214:217], v[4:7]
	v_mfma_f32_16x16x32_bf16 v[32:35], v[168:171], v[222:225], v[32:35]
	v_mfma_f32_16x16x32_bf16 v[0:3], v[176:179], v[222:225], v[0:3]
	v_mfma_f32_16x16x32_bf16 v[56:59], v[172:175], v[202:205], v[56:59]
	v_mfma_f32_16x16x32_bf16 v[24:27], v[194:197], v[202:205], v[24:27]
	v_mfma_f32_16x16x32_bf16 v[40:43], v[172:175], v[210:213], v[40:43]
	v_mfma_f32_16x16x32_bf16 v[12:15], v[194:197], v[210:213], v[12:15]
	v_mfma_f32_16x16x32_bf16 v[36:39], v[172:175], v[218:221], v[36:39]
	v_mfma_f32_16x16x32_bf16 v[4:7], v[194:197], v[218:221], v[4:7]
	v_mfma_f32_16x16x32_bf16 v[32:35], v[172:175], v[226:229], v[32:35]
	v_mfma_f32_16x16x32_bf16 v[0:3], v[194:197], v[226:229], v[0:3]
	s_setprio 0
	s_barrier
	s_add_i32 s78, s78, 2
	s_add_u32 s18, s18, 0x100
	s_addc_u32 s19, s19, 0
	s_add_u32 s76, s76, 0x100
	s_addc_u32 s77, s77, 0
	s_cmp_gt_u32 s78, 29
	s_cbranch_scc0 .LBB0_882
	s_and_b64 vcc, exec, s[30:31]
	s_cbranch_vccz .LBB0_885
	s_barrier
